# FoX layer: Q and K written by the QK GEMM epilogue as MFMA fragment images (1 KiB contiguous per LDS-DMA piece / Q fragment load) instead of 32 rows x 32 B gathers
# speedup vs baseline: 1.0122x; 1.0122x over previous
.LBB0_163:
	s_lshl_b32 s4, s71, 2
	s_add_i32 s40, s4, 0
	s_cmp_gt_i32 s71, 0
	s_cselect_b64 s[28:29], -1, 0
	s_lshl_b32 s6, s71, 5
	s_cmp_lt_i32 s71, 4
	v_lshrrev_b32_e32 v2, 5, v243
	s_cselect_b64 s[4:5], -1, 0
	s_cmp_gt_i32 s71, 3
	v_lshlrev_b32_e32 v166, 3, v2
	v_lshlrev_b32_e32 v2, 4, v2
	v_mov_b32_e32 v3, v0
	s_cselect_b64 s[30:31], -1, 0
	s_lshl_b32 s34, s71, 4
	v_lshlrev_b32_e32 v4, 4, v243
	v_mov_b32_e32 v5, v0
	v_lshl_add_u64 v[168:169], s[96:97], 0, v[4:5]
	v_lshl_add_u64 v[2:3], s[82:83], 0, v[2:3]
	s_add_i32 s7, s34, 0x7fffffc0
	s_and_b32 s78, s6, 32
	v_and_b32_e32 v4, 31, v242
	s_and_b32 s7, s7, 0x7fffffe0
	v_lshl_add_u64 v[170:171], v[2:3], 0, s[78:79]
	v_lshrrev_b32_e32 v2, 1, v242
	v_lshlrev_b32_e32 v3, 1, v243
	v_or_b32_e32 v186, s6, v4
	v_or_b32_e32 v187, s7, v4
	v_and_b32_e32 v2, 4, v2
	v_and_b32_e32 v3, 8, v3
	v_and_b32_e32 v4, 19, v242
	v_and_b32_e32 v1, 64, v238
	v_or3_b32 v188, v2, v4, v3
	v_add_u32_e32 v2, -1, v238
	v_cmp_lt_i32_e32 vcc, v2, v1
	v_mov_b32_e32 v167, v0
	v_lshl_add_u64 v[172:173], s[18:19], 0, v[166:167]
	v_cndmask_b32_e32 v2, v2, v238, vcc
	v_lshlrev_b32_e32 v167, 2, v2
	v_add_u32_e32 v2, -2, v238
	v_cmp_lt_i32_e32 vcc, v2, v1
	s_ashr_i32 s35, s34, 31
	s_and_b64 s[36:37], s[4:5], exec
	v_cndmask_b32_e32 v2, v2, v238, vcc
	v_lshlrev_b32_e32 v190, 2, v2
	v_add_u32_e32 v2, -4, v238
	v_cmp_lt_i32_e32 vcc, v2, v1
	s_cselect_b32 s36, 0x800, 32
	v_readlane_b32 s37, v255, 5
	v_cndmask_b32_e32 v2, v2, v238, vcc
	v_lshlrev_b32_e32 v191, 2, v2
	v_add_u32_e32 v2, -8, v238
	v_cmp_lt_i32_e32 vcc, v2, v1
	v_lshlrev_b32_e32 v184, 3, v242
	v_cmp_eq_u32_e64 s[2:3], 63, v243
	v_cndmask_b32_e32 v2, v2, v238, vcc
	v_lshlrev_b32_e32 v192, 2, v2
	v_add_u32_e32 v2, -16, v238
	v_cmp_lt_i32_e32 vcc, v2, v1
	v_lshl_add_u32 v185, v242, 5, 0
	v_lshl_add_u32 v189, v243, 4, 0
	v_cndmask_b32_e32 v2, v2, v238, vcc
	v_lshlrev_b32_e32 v193, 2, v2
	v_subrev_u32_e32 v2, 32, v238
	v_cmp_lt_i32_e32 vcc, v2, v1
	v_add_u32_e32 v1, 64, v1
	v_cmp_eq_u32_e64 s[6:7], 0, v243
	v_cndmask_b32_e32 v2, v2, v238, vcc
	v_lshlrev_b32_e32 v202, 2, v2
	v_xor_b32_e32 v2, 32, v238
	v_cmp_lt_i32_e32 vcc, v2, v1
	v_cmp_gt_u32_e64 s[8:9], 2, v243
	v_cmp_gt_u32_e64 s[10:11], 4, v243
	v_cndmask_b32_e32 v1, v238, v2, vcc
	v_lshlrev_b32_e32 v203, 2, v1
	v_and_b32_e32 v1, 32, v243
	v_cmp_gt_u32_e64 s[12:13], 8, v243
	v_cmp_gt_u32_e64 s[14:15], 16, v243
	v_cmp_gt_u32_e64 s[16:17], 32, v243
	s_cselect_b32 s41, 6, 0
	v_add_u32_e32 v204, s37, v1
	v_lshlrev_b32_e32 v174, 1, v166
	s_lshl_b32 s36, s36, 1
	s_branch .LBB0_165

.LBB0_170:
	v_pk_add_f32 v[6:7], v[10:11], v[6:7] op_sel_hi:[0,1]
	v_pk_add_f32 v[8:9], v[10:11], v[8:9] op_sel_hi:[0,1]
	v_xor_b32_e32 v7, 0x80000000, v7
	v_xor_b32_e32 v6, 0x80000000, v6
	v_xor_b32_e32 v9, 0x80000000, v9
	v_xor_b32_e32 v8, 0x80000000, v8
	v_pk_add_f32 v[4:5], v[10:11], v[4:5] op_sel_hi:[0,1]
	v_pk_add_f32 v[2:3], v[10:11], v[2:3] op_sel_hi:[0,1]
	ds_write_b128 v185, v[6:9]
	v_xor_b32_e32 v5, 0x80000000, v5
	v_xor_b32_e32 v4, 0x80000000, v4
	v_xor_b32_e32 v7, 0x80000000, v3
	v_xor_b32_e32 v6, 0x80000000, v2
	ds_write_b128 v185, v[4:7] offset:16
	s_lshl_b32 s98, s43, 4
	s_add_i32 s98, s98, s44
	s_lshl_b32 s98, s98, 19
	s_mov_b32 s99, 0
	s_lshl_b32 s100, s71, 10
	s_add_i32 s100, s100, s98
	s_or_b32 s100, s100, 0x4000000
	s_mov_b32 s101, 0
	v_lshlrev_b32_e32 v4, 4, v243
	v_mov_b32_e32 v5, v0
	s_lshl_b32 s38, s44, 6
	s_lshl_b32 s39, s43, 10
	s_lshl_b32 s78, s44, 7
	s_or_b32 s38, s38, s39
	v_lshl_add_u64 v[4:5], s[96:97], 0, v[4:5]
	v_add_u32_e32 v2, s38, v187
	v_lshl_add_u64 v[4:5], v[4:5], 0, s[100:101]
	v_mov_b32_e32 v175, v0
	v_ashrrev_i32_e32 v3, 31, v2
	v_lshlrev_b64 v[2:3], 13, v[2:3]
	v_lshl_add_u64 v[2:3], v[170:171], 0, v[2:3]
	s_and_b32 s42, s33, 1
	v_add_u32_e32 v205, s37, v186
	v_lshl_add_u64 v[176:177], v[168:169], 0, s[98:99]
	v_lshl_add_u64 v[178:179], v[172:173], 0, s[78:79]
	v_cndmask_b32_e64 v181, v3, v5, s[4:5]
	v_cndmask_b32_e64 v180, v2, v4, s[4:5]
	s_mov_b32 s43, 0
	s_waitcnt lgkmcnt(0)
	s_barrier
	s_branch .LBB0_172

.LBB0_172:
	s_and_b32 s38, s43, 6
	s_xor_b32 s38, s38, 15
	s_and_b32 s37, s43, 1
	s_sub_i32 s38, s38, s42
	s_or_b32 s39, s43, s42
	s_cmp_eq_u32 s37, 0
	s_cselect_b32 s38, s39, s38
	s_lshl_b32 s44, s38, 8
	v_add_u32_e32 v182, s44, v205
	v_ashrrev_i32_e32 v183, 31, v182
	v_and_b32_e32 v2, 0xfe0, v182
	v_mov_b32_e32 v3, v0
	v_lshlrev_b64 v[2:3], 7, v[2:3]
	v_lshl_add_u64 v[2:3], v[176:177], 0, v[2:3]
	global_load_dwordx4 v[66:69], v[2:3], off
	global_load_dwordx4 v[70:73], v[2:3], off offset:1024
	global_load_dwordx4 v[74:77], v[2:3], off offset:2048
	global_load_dwordx4 v[78:81], v[2:3], off offset:3072
	s_andn2_b64 vcc, exec, s[30:31]
	s_cbranch_vccnz .LBB0_174
	s_setprio 1

.LBB0_226:
	s_lshr_b32 s98, s33, 2
	s_lshl_b32 s98, s98, 26
	s_lshr_b32 s99, s43, 4
	s_lshl_b32 s99, s99, 4
	s_and_b32 s100, s33, 3
	s_lshl_b32 s100, s100, 2
	s_add_i32 s99, s99, s100
	s_and_b32 s100, s71, 3
	s_lshr_b32 s100, s100, 1
	s_add_i32 s99, s99, s100
	s_lshl_b32 s99, s99, 19
	s_add_u32 s98, s98, s99
	s_add_u32 s98, s96, s98
	s_addc_u32 s99, s97, 0
	s_and_b32 s100, s43, 15
	s_lshl_b32 s100, s100, 15
	s_lshr_b32 s101, s71, 2
	s_lshl_b32 s101, s101, 13
	s_add_i32 s100, s100, s101
	s_and_b32 s101, s71, 1
	s_lshl_b32 s101, s101, 11
	s_add_i32 s100, s100, s101
	v_and_b32_e32 v130, 15, v207
	v_and_b32_e32 v136, 3, v130
	v_and_b32_e32 v137, 4, v130
	v_lshl_or_b32 v136, v137, 1, v136
	v_and_b32_e32 v137, 8, v130
	v_lshrrev_b32_e32 v137, 1, v137
	v_or_b32_e32 v136, v136, v137
	v_cndmask_b32_e64 v130, v136, v130, s[4:5]
	v_lshlrev_b32_e32 v130, 4, v130
	v_and_b32_e32 v136, 31, v147
	v_lshl_add_u32 v130, v136, 6, v130
	v_add_u32_e32 v130, s100, v130
	v_lshrrev_b32_e32 v130, 1, v130
	s_mov_b32 s100, 0x100000
	s_mov_b32 s101, 0
	v_cndmask_b32_e64 v132, 1.0, v240, s[4:5]
	s_andn2_b64 vcc, exec, s[26:27]
	v_ashrrev_i32_e32 v131, 31, v130
	s_cbranch_vccnz .LBB0_228
	v_mul_f32_e32 v134, v132, v224
	v_mov_b64_e32 v[136:137], 0
	v_pk_mul_f32 v[126:127], v[126:127], v[134:135] op_sel_hi:[1,0]
	v_pk_mul_f32 v[128:129], v[128:129], v[134:135] op_sel_hi:[1,0]
	v_pk_mul_f32 v[186:187], v[124:125], v[134:135] op_sel_hi:[1,0]
	v_pk_mul_f32 v[124:125], v[122:123], v[134:135] op_sel_hi:[1,0]
	v_cvt_pk_bf16_f32 v122, v126, v127
	v_lshl_add_u64 v[126:127], s[98:99], 0, v[136:137]
	v_cvt_pk_bf16_f32 v123, v128, v129
	v_cvt_pk_bf16_f32 v124, v124, v125
	v_cvt_pk_bf16_f32 v125, v186, v187
	v_lshl_add_u64 v[126:127], v[130:131], 1, v[126:127]
	global_store_dwordx4 v[126:127], v[122:125], off
	v_pk_mul_f32 v[120:121], v[120:121], v[134:135] op_sel_hi:[1,0]
	v_pk_mul_f32 v[118:119], v[118:119], v[134:135] op_sel_hi:[1,0]
	v_pk_mul_f32 v[122:123], v[116:117], v[134:135] op_sel_hi:[1,0]
	v_pk_mul_f32 v[116:117], v[114:115], v[134:135] op_sel_hi:[1,0]
	v_cvt_pk_bf16_f32 v114, v118, v119
	v_cvt_pk_bf16_f32 v115, v120, v121
	v_cvt_pk_bf16_f32 v116, v116, v117
	v_cvt_pk_bf16_f32 v117, v122, v123
	v_lshl_add_u64 v[126:127], v[126:127], 0, s[100:101]
	global_store_dwordx4 v[126:127], v[114:117], off

.LBB0_232:
	s_andn2_b64 vcc, exec, s[24:25]
	s_cbranch_vccnz .LBB0_234
	v_mul_f32_e32 v114, v132, v122
	v_mov_b64_e32 v[116:117], 0x100
	v_pk_mul_f32 v[110:111], v[110:111], v[114:115] op_sel_hi:[1,0]
	v_pk_mul_f32 v[112:113], v[112:113], v[114:115] op_sel_hi:[1,0]
	v_pk_mul_f32 v[118:119], v[108:109], v[114:115] op_sel_hi:[1,0]
	v_pk_mul_f32 v[108:109], v[106:107], v[114:115] op_sel_hi:[1,0]
	v_cvt_pk_bf16_f32 v106, v110, v111
	v_lshl_add_u64 v[110:111], s[98:99], 0, v[116:117]
	v_cvt_pk_bf16_f32 v107, v112, v113
	v_cvt_pk_bf16_f32 v108, v108, v109
	v_cvt_pk_bf16_f32 v109, v118, v119
	v_lshl_add_u64 v[110:111], v[130:131], 1, v[110:111]
	global_store_dwordx4 v[110:111], v[106:109], off
	v_pk_mul_f32 v[104:105], v[104:105], v[114:115] op_sel_hi:[1,0]
	v_pk_mul_f32 v[102:103], v[102:103], v[114:115] op_sel_hi:[1,0]
	v_pk_mul_f32 v[106:107], v[100:101], v[114:115] op_sel_hi:[1,0]
	v_pk_mul_f32 v[100:101], v[98:99], v[114:115] op_sel_hi:[1,0]
	v_cvt_pk_bf16_f32 v98, v102, v103
	v_cvt_pk_bf16_f32 v99, v104, v105
	v_cvt_pk_bf16_f32 v100, v100, v101
	v_cvt_pk_bf16_f32 v101, v106, v107
	v_lshl_add_u64 v[110:111], v[110:111], 0, s[100:101]
	global_store_dwordx4 v[110:111], v[98:101], off

.LBB0_238:
	s_andn2_b64 vcc, exec, s[24:25]
	s_cbranch_vccnz .LBB0_240
	v_mul_f32_e32 v98, v132, v106
	v_mov_b64_e32 v[100:101], 0x1000
	v_pk_mul_f32 v[94:95], v[94:95], v[98:99] op_sel_hi:[1,0]
	v_pk_mul_f32 v[96:97], v[96:97], v[98:99] op_sel_hi:[1,0]
	v_pk_mul_f32 v[102:103], v[92:93], v[98:99] op_sel_hi:[1,0]
	v_pk_mul_f32 v[92:93], v[90:91], v[98:99] op_sel_hi:[1,0]
	v_cvt_pk_bf16_f32 v90, v94, v95
	v_lshl_add_u64 v[94:95], s[98:99], 0, v[100:101]
	v_cvt_pk_bf16_f32 v91, v96, v97
	v_cvt_pk_bf16_f32 v92, v92, v93
	v_cvt_pk_bf16_f32 v93, v102, v103
	v_lshl_add_u64 v[94:95], v[130:131], 1, v[94:95]
	global_store_dwordx4 v[94:95], v[90:93], off
	v_pk_mul_f32 v[88:89], v[88:89], v[98:99] op_sel_hi:[1,0]
	v_pk_mul_f32 v[86:87], v[86:87], v[98:99] op_sel_hi:[1,0]
	v_pk_mul_f32 v[90:91], v[84:85], v[98:99] op_sel_hi:[1,0]
	v_pk_mul_f32 v[84:85], v[82:83], v[98:99] op_sel_hi:[1,0]
	v_cvt_pk_bf16_f32 v82, v86, v87
	v_cvt_pk_bf16_f32 v83, v88, v89
	v_cvt_pk_bf16_f32 v84, v84, v85
	v_cvt_pk_bf16_f32 v85, v90, v91
	v_lshl_add_u64 v[94:95], v[94:95], 0, s[100:101]
	global_store_dwordx4 v[94:95], v[82:85], off

.LBB0_244:
	s_andn2_b64 vcc, exec, s[24:25]
	s_cbranch_vccnz .LBB0_246
	v_mul_f32_e32 v82, v132, v90
	v_mov_b64_e32 v[84:85], 0x1100
	v_pk_mul_f32 v[78:79], v[78:79], v[82:83] op_sel_hi:[1,0]
	v_pk_mul_f32 v[80:81], v[80:81], v[82:83] op_sel_hi:[1,0]
	v_pk_mul_f32 v[86:87], v[76:77], v[82:83] op_sel_hi:[1,0]
	v_pk_mul_f32 v[76:77], v[74:75], v[82:83] op_sel_hi:[1,0]
	v_cvt_pk_bf16_f32 v74, v78, v79
	v_lshl_add_u64 v[78:79], s[98:99], 0, v[84:85]
	v_cvt_pk_bf16_f32 v75, v80, v81
	v_cvt_pk_bf16_f32 v76, v76, v77
	v_cvt_pk_bf16_f32 v77, v86, v87
	v_lshl_add_u64 v[78:79], v[130:131], 1, v[78:79]
	global_store_dwordx4 v[78:79], v[74:77], off
	v_pk_mul_f32 v[72:73], v[72:73], v[82:83] op_sel_hi:[1,0]
	v_pk_mul_f32 v[70:71], v[70:71], v[82:83] op_sel_hi:[1,0]
	v_pk_mul_f32 v[74:75], v[68:69], v[82:83] op_sel_hi:[1,0]
	v_pk_mul_f32 v[68:69], v[66:67], v[82:83] op_sel_hi:[1,0]
	v_cvt_pk_bf16_f32 v66, v70, v71
	v_cvt_pk_bf16_f32 v67, v72, v73
	v_cvt_pk_bf16_f32 v68, v68, v69
	v_cvt_pk_bf16_f32 v69, v74, v75
	v_lshl_add_u64 v[78:79], v[78:79], 0, s[100:101]
	global_store_dwordx4 v[78:79], v[66:69], off

.LBB0_250:
	s_andn2_b64 vcc, exec, s[24:25]
	s_cbranch_vccnz .LBB0_252
	v_mul_f32_e32 v66, v132, v74
	v_mov_b64_e32 v[68:69], 0x4000
	v_pk_mul_f32 v[62:63], v[62:63], v[66:67] op_sel_hi:[1,0]
	v_pk_mul_f32 v[64:65], v[64:65], v[66:67] op_sel_hi:[1,0]
	v_pk_mul_f32 v[70:71], v[60:61], v[66:67] op_sel_hi:[1,0]
	v_pk_mul_f32 v[60:61], v[58:59], v[66:67] op_sel_hi:[1,0]
	v_cvt_pk_bf16_f32 v58, v62, v63
	v_lshl_add_u64 v[62:63], s[98:99], 0, v[68:69]
	v_cvt_pk_bf16_f32 v59, v64, v65
	v_cvt_pk_bf16_f32 v60, v60, v61
	v_cvt_pk_bf16_f32 v61, v70, v71
	v_lshl_add_u64 v[62:63], v[130:131], 1, v[62:63]
	global_store_dwordx4 v[62:63], v[58:61], off
	v_pk_mul_f32 v[56:57], v[56:57], v[66:67] op_sel_hi:[1,0]
	v_pk_mul_f32 v[54:55], v[54:55], v[66:67] op_sel_hi:[1,0]
	v_pk_mul_f32 v[58:59], v[52:53], v[66:67] op_sel_hi:[1,0]
	v_pk_mul_f32 v[52:53], v[50:51], v[66:67] op_sel_hi:[1,0]
	v_cvt_pk_bf16_f32 v50, v54, v55
	v_cvt_pk_bf16_f32 v51, v56, v57
	v_cvt_pk_bf16_f32 v52, v52, v53
	v_cvt_pk_bf16_f32 v53, v58, v59
	v_lshl_add_u64 v[62:63], v[62:63], 0, s[100:101]
	global_store_dwordx4 v[62:63], v[50:53], off

.LBB0_256:
	s_andn2_b64 vcc, exec, s[24:25]
	s_cbranch_vccnz .LBB0_258
	v_mul_f32_e32 v50, v132, v58
	v_mov_b64_e32 v[52:53], 0x4100
	v_pk_mul_f32 v[46:47], v[46:47], v[50:51] op_sel_hi:[1,0]
	v_pk_mul_f32 v[48:49], v[48:49], v[50:51] op_sel_hi:[1,0]
	v_pk_mul_f32 v[54:55], v[44:45], v[50:51] op_sel_hi:[1,0]
	v_pk_mul_f32 v[44:45], v[42:43], v[50:51] op_sel_hi:[1,0]
	v_cvt_pk_bf16_f32 v42, v46, v47
	v_lshl_add_u64 v[46:47], s[98:99], 0, v[52:53]
	v_cvt_pk_bf16_f32 v43, v48, v49
	v_cvt_pk_bf16_f32 v44, v44, v45
	v_cvt_pk_bf16_f32 v45, v54, v55
	v_lshl_add_u64 v[46:47], v[130:131], 1, v[46:47]
	global_store_dwordx4 v[46:47], v[42:45], off
	v_pk_mul_f32 v[40:41], v[40:41], v[50:51] op_sel_hi:[1,0]
	v_pk_mul_f32 v[38:39], v[38:39], v[50:51] op_sel_hi:[1,0]
	v_pk_mul_f32 v[42:43], v[36:37], v[50:51] op_sel_hi:[1,0]
	v_pk_mul_f32 v[36:37], v[34:35], v[50:51] op_sel_hi:[1,0]
	v_cvt_pk_bf16_f32 v34, v38, v39
	v_cvt_pk_bf16_f32 v35, v40, v41
	v_cvt_pk_bf16_f32 v36, v36, v37
	v_cvt_pk_bf16_f32 v37, v42, v43
	v_lshl_add_u64 v[46:47], v[46:47], 0, s[100:101]
	global_store_dwordx4 v[46:47], v[34:37], off

.LBB0_262:
	s_andn2_b64 vcc, exec, s[24:25]
	s_cbranch_vccnz .LBB0_264
	v_mul_f32_e32 v34, v132, v42
	v_mov_b64_e32 v[36:37], 0x5000
	v_pk_mul_f32 v[30:31], v[30:31], v[34:35] op_sel_hi:[1,0]
	v_pk_mul_f32 v[32:33], v[32:33], v[34:35] op_sel_hi:[1,0]
	v_pk_mul_f32 v[38:39], v[28:29], v[34:35] op_sel_hi:[1,0]
	v_pk_mul_f32 v[28:29], v[26:27], v[34:35] op_sel_hi:[1,0]
	v_cvt_pk_bf16_f32 v26, v30, v31
	v_lshl_add_u64 v[30:31], s[98:99], 0, v[36:37]
	v_cvt_pk_bf16_f32 v27, v32, v33
	v_cvt_pk_bf16_f32 v28, v28, v29
	v_cvt_pk_bf16_f32 v29, v38, v39
	v_lshl_add_u64 v[30:31], v[130:131], 1, v[30:31]
	global_store_dwordx4 v[30:31], v[26:29], off
	v_pk_mul_f32 v[24:25], v[24:25], v[34:35] op_sel_hi:[1,0]
	v_pk_mul_f32 v[22:23], v[22:23], v[34:35] op_sel_hi:[1,0]
	v_pk_mul_f32 v[26:27], v[20:21], v[34:35] op_sel_hi:[1,0]
	v_pk_mul_f32 v[20:21], v[18:19], v[34:35] op_sel_hi:[1,0]
	v_cvt_pk_bf16_f32 v18, v22, v23
	v_cvt_pk_bf16_f32 v19, v24, v25
	v_cvt_pk_bf16_f32 v20, v20, v21
	v_cvt_pk_bf16_f32 v21, v26, v27
	v_lshl_add_u64 v[30:31], v[30:31], 0, s[100:101]
	global_store_dwordx4 v[30:31], v[18:21], off

.LBB0_270:
	v_mul_f32_e32 v18, v132, v26
	v_mov_b64_e32 v[20:21], 0x5100
	v_pk_mul_f32 v[14:15], v[14:15], v[18:19] op_sel_hi:[1,0]
	v_pk_mul_f32 v[16:17], v[16:17], v[18:19] op_sel_hi:[1,0]
	v_pk_mul_f32 v[22:23], v[12:13], v[18:19] op_sel_hi:[1,0]
	v_pk_mul_f32 v[12:13], v[10:11], v[18:19] op_sel_hi:[1,0]
	v_cvt_pk_bf16_f32 v10, v14, v15
	v_lshl_add_u64 v[14:15], s[98:99], 0, v[20:21]
	v_cvt_pk_bf16_f32 v11, v16, v17
	v_cvt_pk_bf16_f32 v12, v12, v13
	v_cvt_pk_bf16_f32 v13, v22, v23
	v_lshl_add_u64 v[14:15], v[130:131], 1, v[14:15]
	global_store_dwordx4 v[14:15], v[10:13], off
	v_pk_mul_f32 v[8:9], v[8:9], v[18:19] op_sel_hi:[1,0]
	v_pk_mul_f32 v[6:7], v[6:7], v[18:19] op_sel_hi:[1,0]
	v_pk_mul_f32 v[10:11], v[4:5], v[18:19] op_sel_hi:[1,0]
	v_pk_mul_f32 v[4:5], v[2:3], v[18:19] op_sel_hi:[1,0]
	v_cvt_pk_bf16_f32 v2, v6, v7
	v_cvt_pk_bf16_f32 v3, v8, v9
	v_cvt_pk_bf16_f32 v4, v4, v5
	v_cvt_pk_bf16_f32 v5, v10, v11
	v_lshl_add_u64 v[14:15], v[14:15], 0, s[100:101]
	global_store_dwordx4 v[14:15], v[2:5], off
	s_andn2_b64 vcc, exec, s[2:3]
	s_mov_b64 s[2:3], -1
	s_cbranch_vccnz .LBB0_211
